# opt14 + diff-attention loop: fused path - PV(a) 16 MFMAs interleaved with the exp part of softmax(b) (P(b) packed in place, O rescale deferred behind PV(a))
# baseline (speedup 1.0000x reference)
; template <bool SWA>
; __device__ __forceinline__ void unit(LAS unsigned char* lds, const bf16_t* PROJ, const bf16_t* KT, const bf16_t* VT, bf16_t* OB, int opitch, int ocol, int b, int head, int qb, float slope2, float m_init, float lam, const float* subg) {
;     ...
;         if (acta) { SM_T(s0, s1, kva, clsa); if (pvalid) PV_TILE(sa); }
;         if (actb) { SM_T(u0, u1, kvb, clsb); if (pvalid) PV_TILE(sb); }
.LBB0_900:
	v_sub_f32_e32 v145, v174, v204
	v_sub_f32_e32 v146, v174, v205
	v_sub_f32_e32 v112, v112, v145
	v_sub_f32_e32 v96, v96, v146
	v_exp_f32_e32 v112, v112
	v_exp_f32_e32 v96, v96
	v_sub_f32_e32 v113, v113, v145
	v_sub_f32_e32 v97, v97, v146
	v_exp_f32_e32 v113, v113
	v_exp_f32_e32 v97, v97
	v_sub_f32_e32 v114, v114, v145
	v_sub_f32_e32 v98, v98, v146
	v_exp_f32_e32 v114, v114
	v_exp_f32_e32 v98, v98
	v_sub_f32_e32 v115, v115, v145
	v_sub_f32_e32 v99, v99, v146
	v_exp_f32_e32 v115, v115
	v_exp_f32_e32 v99, v99
	v_sub_f32_e32 v116, v116, v145
	v_sub_f32_e32 v100, v100, v146
	v_exp_f32_e32 v116, v116
	v_exp_f32_e32 v100, v100
	v_sub_f32_e32 v117, v117, v145
	v_sub_f32_e32 v101, v101, v146
	v_add_f32_e32 v147, v113, v112
	v_add_f32_e32 v148, v97, v96
	v_exp_f32_e32 v117, v117
	v_exp_f32_e32 v101, v101
	v_sub_f32_e32 v118, v118, v145
	v_sub_f32_e32 v102, v102, v146
	v_add_f32_e32 v147, v114, v147
	v_add_f32_e32 v148, v98, v148
	v_exp_f32_e32 v118, v118
	v_exp_f32_e32 v102, v102
	v_sub_f32_e32 v119, v119, v145
	v_sub_f32_e32 v103, v103, v146
	v_add_f32_e32 v147, v115, v147
	v_add_f32_e32 v148, v99, v148
	v_exp_f32_e32 v119, v119
	v_exp_f32_e32 v103, v103
	v_sub_f32_e32 v120, v120, v145
	v_sub_f32_e32 v104, v104, v146
	v_add_f32_e32 v147, v116, v147
	v_add_f32_e32 v148, v100, v148
	v_exp_f32_e32 v120, v120
	v_exp_f32_e32 v104, v104
	v_sub_f32_e32 v121, v121, v145
	v_sub_f32_e32 v105, v105, v146
	v_add_f32_e32 v147, v117, v147
	v_add_f32_e32 v148, v101, v148
	v_exp_f32_e32 v121, v121
	v_exp_f32_e32 v105, v105
	v_sub_f32_e32 v122, v122, v145
	v_sub_f32_e32 v106, v106, v146
	v_add_f32_e32 v147, v118, v147
	v_add_f32_e32 v148, v102, v148
	v_exp_f32_e32 v122, v122
	v_exp_f32_e32 v106, v106
	v_sub_f32_e32 v123, v123, v145
	v_sub_f32_e32 v107, v107, v146
	v_add_f32_e32 v147, v119, v147
	v_add_f32_e32 v148, v103, v148
	v_exp_f32_e32 v123, v123
	v_exp_f32_e32 v107, v107
	v_sub_f32_e32 v124, v124, v145
	v_sub_f32_e32 v108, v108, v146
	v_add_f32_e32 v147, v120, v147
	v_add_f32_e32 v148, v104, v148
	v_exp_f32_e32 v124, v124
	v_exp_f32_e32 v108, v108
	v_sub_f32_e32 v125, v125, v145
	v_sub_f32_e32 v109, v109, v146
	v_add_f32_e32 v147, v121, v147
	v_add_f32_e32 v148, v105, v148
	v_exp_f32_e32 v125, v125
	v_exp_f32_e32 v109, v109
	v_sub_f32_e32 v126, v126, v145
	v_sub_f32_e32 v110, v110, v146
	v_add_f32_e32 v147, v122, v147
	v_add_f32_e32 v148, v106, v148
	v_exp_f32_e32 v126, v126
	v_exp_f32_e32 v110, v110
	v_sub_f32_e32 v127, v127, v145
	v_sub_f32_e32 v111, v111, v146
	v_add_f32_e32 v147, v123, v147
	v_add_f32_e32 v148, v107, v148
	v_exp_f32_e32 v127, v127
	v_exp_f32_e32 v111, v111
	v_add_f32_e32 v147, v124, v147
	v_add_f32_e32 v148, v108, v148
	v_add_f32_e32 v147, v125, v147
	v_add_f32_e32 v148, v109, v148
	v_add_f32_e32 v145, v126, v147
	v_add_f32_e32 v146, v110, v148
	v_add_f32_e32 v145, v127, v145
	v_add_f32_e32 v146, v111, v146
	v_add_f32_e32 v179, v145, v146
	v_fma_f32 v193, v193, v144, v179
	v_cvt_pk_bf16_f32 v144, v112, v113
	v_cvt_pk_bf16_f32 v145, v114, v115
	v_cvt_pk_bf16_f32 v146, v116, v117
	v_cvt_pk_bf16_f32 v147, v118, v119
	v_cvt_pk_bf16_f32 v148, v120, v121
	v_cvt_pk_bf16_f32 v149, v122, v123
	v_cvt_pk_bf16_f32 v150, v124, v125
	v_cvt_pk_bf16_f32 v151, v126, v127
	v_cvt_pk_bf16_f32 v152, v96, v97
	v_cvt_pk_bf16_f32 v153, v98, v99
	v_cvt_pk_bf16_f32 v154, v100, v101
	v_cvt_pk_bf16_f32 v155, v102, v103
	v_cvt_pk_bf16_f32 v156, v104, v105
	v_cvt_pk_bf16_f32 v157, v106, v107
	v_cvt_pk_bf16_f32 v158, v108, v109
	v_cvt_pk_bf16_f32 v159, v110, v111
	s_xor_b64 s[80:81], s[80:81], -1
	s_andn2_b64 vcc, exec, s[82:83]
	s_cbranch_vccnz .LBB0_903
	s_and_b64 vcc, exec, s[80:81]
	s_cbranch_vccz .LBB0_902
	s_branch .Lfz_entry

.Lfz_entry:
	s_add_i32 s29, s29, 0x10000
	v_add_u32_e32 v241, s29, v189
	v_add_u32_e32 v242, s29, v190
	v_add_u32_e32 v243, s29, v191
	v_add_u32_e32 v244, s29, v192
	ds_read_b128 v[96:99], v241
	ds_read_b128 v[100:103], v241 offset:4096
	ds_read_b128 v[104:107], v242
	ds_read_b128 v[108:111], v242 offset:4096
	ds_read_b128 v[112:115], v243
	ds_read_b128 v[116:119], v243 offset:4096
	ds_read_b128 v[120:123], v244
	ds_read_b128 v[124:127], v244 offset:4096
	v_or_b32_e32 v236, s28, v187
	v_sub_u32_e32 v236, v188, v236
	v_cvt_f32_i32_e32 v236, v236
	s_andn2_b64 vcc, exec, s[78:79]
	s_cbranch_vccnz .Lfz_right
	v_mul_f32_e64 v237, -s76, v236
	v_fma_f32 v238, -s76, v236, v194
	s_branch .Lfz_max
.Lfz_right:
	v_mul_f32_e32 v237, s76, v236
	v_fma_f32 v238, s76, v236, -v194
.Lfz_max:
	v_max_f32_e32 v236, v81, v81
	v_max_f32_e32 v239, v80, v80
	v_max_f32_e32 v236, v239, v236
	v_max_f32_e32 v239, v65, v65
	v_max_f32_e32 v240, v64, v64
	v_max_f32_e32 v239, v240, v239
	v_max3_f32 v236, v236, v82, v83
	v_max3_f32 v239, v239, v66, v67
	v_max3_f32 v236, v236, v84, v85
	v_max3_f32 v239, v239, v68, v69
	v_max3_f32 v236, v236, v86, v87
	v_max3_f32 v239, v239, v70, v71
	v_max3_f32 v236, v236, v88, v89
	v_max3_f32 v239, v239, v72, v73
	v_max3_f32 v236, v236, v90, v91
	v_max3_f32 v239, v239, v74, v75
	v_max3_f32 v236, v236, v92, v93
	v_max3_f32 v239, v239, v76, v77
	v_max3_f32 v236, v236, v94, v95
	v_max3_f32 v239, v239, v78, v79
	v_add_f32_e32 v236, v237, v236
	v_add_f32_e32 v239, v238, v239
	v_max_f32_e32 v236, v236, v239
	v_mov_b32_e32 v239, v236
	s_nop 1
	v_permlane32_swap_b32_e32 v236, v239
	v_max_f32_e32 v239, v239, v239
	v_max_f32_e32 v236, v236, v236
	v_max_f32_e32 v236, v236, v239
	v_sub_f32_e32 v239, v236, v174
	v_cmp_gt_f32_e32 vcc, s18, v239
	s_cmp_lg_u64 vcc, exec
	s_cselect_b64 s[78:79], -1, 0
	s_cmp_eq_u64 vcc, exec
	s_cbranch_scc1 .Lfz_skipb
	v_max_f32_e32 v236, v236, v236
	v_max_f32_e32 v239, v174, v174
	v_max_f32_e32 v203, v239, v236
	v_sub_f32_e32 v236, v174, v203
	v_exp_f32_e32 v236, v236
	s_nop 0
	v_cmp_neq_f32_e32 vcc, 1.0, v236
	s_mov_b64 s[6:7], vcc
	s_setprio 1
	s_waitcnt lgkmcnt(7)
	v_mfma_f32_32x32x16_bf16 v[16:31], v[96:99], v[144:147], v[16:31]
	ds_read_b128 v[96:99], v241 offset:8192
	v_sub_f32_e32 v237, v203, v237
	v_sub_f32_e32 v238, v203, v238
	v_sub_f32_e32 v80, v80, v237
	v_sub_f32_e32 v64, v64, v238
	v_exp_f32_e32 v80, v80
	v_exp_f32_e32 v64, v64
	v_sub_f32_e32 v81, v81, v237
	v_sub_f32_e32 v65, v65, v238
	s_waitcnt lgkmcnt(7)
	v_mfma_f32_32x32x16_bf16 v[48:63], v[100:103], v[144:147], v[48:63]
	ds_read_b128 v[100:103], v241 offset:12288
	v_exp_f32_e32 v81, v81
	v_exp_f32_e32 v65, v65
	v_sub_f32_e32 v82, v82, v237
	v_sub_f32_e32 v66, v66, v238
	v_exp_f32_e32 v82, v82
	v_exp_f32_e32 v66, v66
	v_sub_f32_e32 v83, v83, v237
	v_sub_f32_e32 v67, v67, v238
	s_waitcnt lgkmcnt(7)
	v_mfma_f32_32x32x16_bf16 v[16:31], v[104:107], v[148:151], v[16:31]
	ds_read_b128 v[104:107], v242 offset:8192
	v_exp_f32_e32 v83, v83
	v_exp_f32_e32 v67, v67
	v_sub_f32_e32 v84, v84, v237
	v_sub_f32_e32 v68, v68, v238
	v_add_f32_e32 v239, 0, v80
	v_add_f32_e32 v240, 0, v64
	v_exp_f32_e32 v84, v84
	v_exp_f32_e32 v68, v68
	s_waitcnt lgkmcnt(7)
	v_mfma_f32_32x32x16_bf16 v[48:63], v[108:111], v[148:151], v[48:63]
	ds_read_b128 v[108:111], v242 offset:12288
	v_sub_f32_e32 v85, v85, v237
	v_sub_f32_e32 v69, v69, v238
	v_add_f32_e32 v239, v81, v239
	v_add_f32_e32 v240, v65, v240
	v_exp_f32_e32 v85, v85
	v_exp_f32_e32 v69, v69
	v_sub_f32_e32 v86, v86, v237
	v_sub_f32_e32 v70, v70, v238
	s_waitcnt lgkmcnt(7)
	v_mfma_f32_32x32x16_bf16 v[16:31], v[112:115], v[152:155], v[16:31]
	ds_read_b128 v[112:115], v243 offset:8192
	v_add_f32_e32 v239, v82, v239
	v_add_f32_e32 v240, v66, v240
	v_exp_f32_e32 v86, v86
	v_exp_f32_e32 v70, v70
	v_sub_f32_e32 v87, v87, v237
	v_sub_f32_e32 v71, v71, v238
	v_add_f32_e32 v239, v83, v239
	v_add_f32_e32 v240, v67, v240
	s_waitcnt lgkmcnt(7)
	v_mfma_f32_32x32x16_bf16 v[48:63], v[116:119], v[152:155], v[48:63]
	ds_read_b128 v[116:119], v243 offset:12288
	v_exp_f32_e32 v87, v87
	v_exp_f32_e32 v71, v71
	v_sub_f32_e32 v88, v88, v237
	v_sub_f32_e32 v72, v72, v238
	v_add_f32_e32 v239, v84, v239
	v_add_f32_e32 v240, v68, v240
	v_exp_f32_e32 v88, v88
	v_exp_f32_e32 v72, v72
	s_waitcnt lgkmcnt(7)
	v_mfma_f32_32x32x16_bf16 v[16:31], v[120:123], v[156:159], v[16:31]
	ds_read_b128 v[120:123], v244 offset:8192
	v_sub_f32_e32 v89, v89, v237
	v_sub_f32_e32 v73, v73, v238
	v_add_f32_e32 v239, v85, v239
	v_add_f32_e32 v240, v69, v240
	v_exp_f32_e32 v89, v89
	v_exp_f32_e32 v73, v73
	v_sub_f32_e32 v90, v90, v237
	v_sub_f32_e32 v74, v74, v238
	s_waitcnt lgkmcnt(7)
	v_mfma_f32_32x32x16_bf16 v[48:63], v[124:127], v[156:159], v[48:63]
	ds_read_b128 v[124:127], v244 offset:12288
	v_add_f32_e32 v239, v86, v239
	v_add_f32_e32 v240, v70, v240
	v_exp_f32_e32 v90, v90
	v_exp_f32_e32 v74, v74
	v_sub_f32_e32 v91, v91, v237
	v_sub_f32_e32 v75, v75, v238
	v_add_f32_e32 v239, v87, v239
	v_add_f32_e32 v240, v71, v240
	s_waitcnt lgkmcnt(7)
	v_mfma_f32_32x32x16_bf16 v[32:47], v[96:99], v[144:147], v[32:47]
	v_exp_f32_e32 v91, v91
	v_exp_f32_e32 v75, v75
	v_sub_f32_e32 v92, v92, v237
	v_sub_f32_e32 v76, v76, v238
	v_add_f32_e32 v239, v88, v239
	v_add_f32_e32 v240, v72, v240
	v_exp_f32_e32 v92, v92
	v_exp_f32_e32 v76, v76
	s_waitcnt lgkmcnt(6)
	v_mfma_f32_32x32x16_bf16 v[0:15], v[100:103], v[144:147], v[0:15]
	v_sub_f32_e32 v93, v93, v237
	v_sub_f32_e32 v77, v77, v238
	v_add_f32_e32 v239, v89, v239
	v_add_f32_e32 v240, v73, v240
	v_exp_f32_e32 v93, v93
	v_exp_f32_e32 v77, v77
	v_sub_f32_e32 v94, v94, v237
	v_sub_f32_e32 v78, v78, v238
	s_waitcnt lgkmcnt(5)
	v_mfma_f32_32x32x16_bf16 v[32:47], v[104:107], v[148:151], v[32:47]
	v_add_f32_e32 v239, v90, v239
	v_add_f32_e32 v240, v74, v240
	v_exp_f32_e32 v94, v94
	v_exp_f32_e32 v78, v78
	v_sub_f32_e32 v95, v95, v237
	v_sub_f32_e32 v79, v79, v238
	v_add_f32_e32 v239, v91, v239
	v_add_f32_e32 v240, v75, v240
	s_waitcnt lgkmcnt(4)
	v_mfma_f32_32x32x16_bf16 v[0:15], v[108:111], v[148:151], v[0:15]
	v_exp_f32_e32 v95, v95
	v_exp_f32_e32 v79, v79
	v_add_f32_e32 v239, v92, v239
	v_add_f32_e32 v240, v76, v240
	v_add_f32_e32 v239, v93, v239
	v_add_f32_e32 v240, v77, v240
	v_add_f32_e32 v237, v94, v239
	v_add_f32_e32 v238, v78, v240
	s_waitcnt lgkmcnt(3)
	v_mfma_f32_32x32x16_bf16 v[32:47], v[112:115], v[152:155], v[32:47]
	v_add_f32_e32 v237, v95, v237
	v_add_f32_e32 v238, v79, v238
	v_add_f32_e32 v237, v237, v238
	v_fmac_f32_e32 v237, v193, v236
	v_cvt_pk_bf16_f32 v80, v80, v81
	v_cvt_pk_bf16_f32 v81, v82, v83
	v_cvt_pk_bf16_f32 v82, v84, v85
	v_cvt_pk_bf16_f32 v83, v86, v87
	s_waitcnt lgkmcnt(2)
	v_mfma_f32_32x32x16_bf16 v[0:15], v[116:119], v[152:155], v[0:15]
	v_cvt_pk_bf16_f32 v84, v88, v89
	v_cvt_pk_bf16_f32 v85, v90, v91
	v_cvt_pk_bf16_f32 v86, v92, v93
	v_cvt_pk_bf16_f32 v87, v94, v95
	v_cvt_pk_bf16_f32 v64, v64, v65
	v_cvt_pk_bf16_f32 v65, v66, v67
	v_cvt_pk_bf16_f32 v66, v68, v69
	v_cvt_pk_bf16_f32 v67, v70, v71
	s_waitcnt lgkmcnt(1)
	v_mfma_f32_32x32x16_bf16 v[32:47], v[120:123], v[156:159], v[32:47]
	v_cvt_pk_bf16_f32 v68, v72, v73
	v_cvt_pk_bf16_f32 v69, v74, v75
	v_cvt_pk_bf16_f32 v70, v76, v77
	v_cvt_pk_bf16_f32 v71, v78, v79
	v_mov_b32_e32 v193, v237
	s_waitcnt lgkmcnt(0)
	v_mfma_f32_32x32x16_bf16 v[0:15], v[124:127], v[156:159], v[0:15]
	s_setprio 0
	s_and_b64 vcc, exec, s[6:7]
	s_cbranch_vccz .Lfz_nors
	s_nop 7
	s_nop 3
	v_mul_f32_e32 v0, v236, v0
	v_mul_f32_e32 v1, v236, v1
	v_mul_f32_e32 v2, v236, v2
	v_mul_f32_e32 v3, v236, v3
	v_mul_f32_e32 v4, v236, v4
	v_mul_f32_e32 v5, v236, v5
	v_mul_f32_e32 v6, v236, v6
	v_mul_f32_e32 v7, v236, v7
	v_mul_f32_e32 v8, v236, v8
	v_mul_f32_e32 v9, v236, v9
	v_mul_f32_e32 v10, v236, v10
	v_mul_f32_e32 v11, v236, v11
	v_mul_f32_e32 v12, v236, v12
	v_mul_f32_e32 v13, v236, v13
	v_mul_f32_e32 v14, v236, v14
	v_mul_f32_e32 v15, v236, v15
	v_mul_f32_e32 v16, v236, v16
	v_mul_f32_e32 v17, v236, v17
	v_mul_f32_e32 v18, v236, v18
	v_mul_f32_e32 v19, v236, v19
	v_mul_f32_e32 v20, v236, v20
	v_mul_f32_e32 v21, v236, v21
	v_mul_f32_e32 v22, v236, v22
	v_mul_f32_e32 v23, v236, v23
	v_mul_f32_e32 v24, v236, v24
	v_mul_f32_e32 v25, v236, v25
	v_mul_f32_e32 v26, v236, v26
	v_mul_f32_e32 v27, v236, v27
	v_mul_f32_e32 v28, v236, v28
	v_mul_f32_e32 v29, v236, v29
	v_mul_f32_e32 v30, v236, v30
	v_mul_f32_e32 v31, v236, v31
	v_mul_f32_e32 v32, v236, v32
	v_mul_f32_e32 v33, v236, v33
	v_mul_f32_e32 v34, v236, v34
	v_mul_f32_e32 v35, v236, v35
	v_mul_f32_e32 v36, v236, v36
	v_mul_f32_e32 v37, v236, v37
	v_mul_f32_e32 v38, v236, v38
	v_mul_f32_e32 v39, v236, v39
	v_mul_f32_e32 v40, v236, v40
	v_mul_f32_e32 v41, v236, v41
	v_mul_f32_e32 v42, v236, v42
	v_mul_f32_e32 v43, v236, v43
	v_mul_f32_e32 v44, v236, v44
	v_mul_f32_e32 v45, v236, v45
	v_mul_f32_e32 v46, v236, v46
	v_mul_f32_e32 v47, v236, v47
	v_mul_f32_e32 v48, v236, v48
	v_mul_f32_e32 v49, v236, v49
	v_mul_f32_e32 v50, v236, v50
	v_mul_f32_e32 v51, v236, v51
	v_mul_f32_e32 v52, v236, v52
	v_mul_f32_e32 v53, v236, v53
	v_mul_f32_e32 v54, v236, v54
	v_mul_f32_e32 v55, v236, v55
	v_mul_f32_e32 v56, v236, v56
	v_mul_f32_e32 v57, v236, v57
	v_mul_f32_e32 v58, v236, v58
	v_mul_f32_e32 v59, v236, v59
	v_mul_f32_e32 v60, v236, v60
	v_mul_f32_e32 v61, v236, v61
	v_mul_f32_e32 v62, v236, v62
	v_mul_f32_e32 v63, v236, v63
; template <bool SWA>
; __device__ __forceinline__ void unit(LAS unsigned char* lds, const bf16_t* PROJ, const bf16_t* KT, const bf16_t* VT, bf16_t* OB, int opitch, int ocol, int b, int head, int qb, float slope2, float m_init, float lam, const float* subg) {
;     ...
;         if (acta) { SM_T(s0, s1, kva, clsa); if (pvalid) PV_TILE(sa); }
;         if (actb) { SM_T(u0, u1, kvb, clsb); if (pvalid) PV_TILE(sb); }
.Lfz_nors:
	s_add_i32 s27, s27, 0x10000
	v_add_u32_e32 v241, s27, v189
	v_add_u32_e32 v242, s27, v190
	v_add_u32_e32 v243, s27, v191
	v_add_u32_e32 v244, s27, v192
	ds_read_b128 v[96:99], v241
	ds_read_b128 v[100:103], v241 offset:4096
	ds_read_b128 v[104:107], v242
	ds_read_b128 v[108:111], v242 offset:4096
	ds_read_b128 v[112:115], v243
	ds_read_b128 v[116:119], v243 offset:4096
	ds_read_b128 v[120:123], v244
	ds_read_b128 v[124:127], v244 offset:4096
	s_setprio 1
	s_waitcnt lgkmcnt(7)
	v_mfma_f32_32x32x16_bf16 v[16:31], v[96:99], v[80:83], v[16:31]
	ds_read_b128 v[96:99], v241 offset:8192
	s_waitcnt lgkmcnt(7)
	v_mfma_f32_32x32x16_bf16 v[48:63], v[100:103], v[80:83], v[48:63]
	ds_read_b128 v[100:103], v241 offset:12288
	s_waitcnt lgkmcnt(7)
	v_mfma_f32_32x32x16_bf16 v[16:31], v[104:107], v[84:87], v[16:31]
	ds_read_b128 v[104:107], v242 offset:8192
	s_waitcnt lgkmcnt(7)
	v_mfma_f32_32x32x16_bf16 v[48:63], v[108:111], v[84:87], v[48:63]
	ds_read_b128 v[108:111], v242 offset:12288
	s_waitcnt lgkmcnt(7)
	v_mfma_f32_32x32x16_bf16 v[16:31], v[112:115], v[64:67], v[16:31]
	ds_read_b128 v[112:115], v243 offset:8192
	s_waitcnt lgkmcnt(7)
	v_mfma_f32_32x32x16_bf16 v[48:63], v[116:119], v[64:67], v[48:63]
	ds_read_b128 v[116:119], v243 offset:12288
	s_waitcnt lgkmcnt(7)
	v_mfma_f32_32x32x16_bf16 v[16:31], v[120:123], v[68:71], v[16:31]
	ds_read_b128 v[120:123], v244 offset:8192
	s_waitcnt lgkmcnt(7)
	v_mfma_f32_32x32x16_bf16 v[48:63], v[124:127], v[68:71], v[48:63]
	ds_read_b128 v[124:127], v244 offset:12288
	s_waitcnt lgkmcnt(7)
	v_mfma_f32_32x32x16_bf16 v[32:47], v[96:99], v[80:83], v[32:47]
	s_waitcnt lgkmcnt(6)
	v_mfma_f32_32x32x16_bf16 v[0:15], v[100:103], v[80:83], v[0:15]
	s_waitcnt lgkmcnt(5)
	v_mfma_f32_32x32x16_bf16 v[32:47], v[104:107], v[84:87], v[32:47]
	s_waitcnt lgkmcnt(4)
	v_mfma_f32_32x32x16_bf16 v[0:15], v[108:111], v[84:87], v[0:15]
	s_waitcnt lgkmcnt(3)
	v_mfma_f32_32x32x16_bf16 v[32:47], v[112:115], v[64:67], v[32:47]
	s_waitcnt lgkmcnt(2)
	v_mfma_f32_32x32x16_bf16 v[0:15], v[116:119], v[64:67], v[0:15]
	s_waitcnt lgkmcnt(1)
	v_mfma_f32_32x32x16_bf16 v[32:47], v[120:123], v[68:71], v[32:47]
	s_waitcnt lgkmcnt(0)
	v_mfma_f32_32x32x16_bf16 v[0:15], v[124:127], v[68:71], v[0:15]
	s_setprio 0
	s_branch .LBB0_883
.Lfz_skipb:
	v_mov_b32_e32 v203, v174
	s_setprio 1
	s_waitcnt lgkmcnt(7)
	v_mfma_f32_32x32x16_bf16 v[16:31], v[96:99], v[144:147], v[16:31]
	ds_read_b128 v[96:99], v241 offset:8192
	s_waitcnt lgkmcnt(7)
	v_mfma_f32_32x32x16_bf16 v[48:63], v[100:103], v[144:147], v[48:63]
	ds_read_b128 v[100:103], v241 offset:12288
	s_waitcnt lgkmcnt(7)
	v_mfma_f32_32x32x16_bf16 v[16:31], v[104:107], v[148:151], v[16:31]
	ds_read_b128 v[104:107], v242 offset:8192
	s_waitcnt lgkmcnt(7)
	v_mfma_f32_32x32x16_bf16 v[48:63], v[108:111], v[148:151], v[48:63]
	ds_read_b128 v[108:111], v242 offset:12288
	s_waitcnt lgkmcnt(7)
	v_mfma_f32_32x32x16_bf16 v[16:31], v[112:115], v[152:155], v[16:31]
	ds_read_b128 v[112:115], v243 offset:8192
	s_waitcnt lgkmcnt(7)
	v_mfma_f32_32x32x16_bf16 v[48:63], v[116:119], v[152:155], v[48:63]
	ds_read_b128 v[116:119], v243 offset:12288
	s_waitcnt lgkmcnt(7)
	v_mfma_f32_32x32x16_bf16 v[16:31], v[120:123], v[156:159], v[16:31]
	ds_read_b128 v[120:123], v244 offset:8192
	s_waitcnt lgkmcnt(7)
	v_mfma_f32_32x32x16_bf16 v[48:63], v[124:127], v[156:159], v[48:63]
	ds_read_b128 v[124:127], v244 offset:12288
	s_waitcnt lgkmcnt(7)
	v_mfma_f32_32x32x16_bf16 v[32:47], v[96:99], v[144:147], v[32:47]
	s_waitcnt lgkmcnt(6)
	v_mfma_f32_32x32x16_bf16 v[0:15], v[100:103], v[144:147], v[0:15]
	s_waitcnt lgkmcnt(5)
	v_mfma_f32_32x32x16_bf16 v[32:47], v[104:107], v[148:151], v[32:47]
	s_waitcnt lgkmcnt(4)
	v_mfma_f32_32x32x16_bf16 v[0:15], v[108:111], v[148:151], v[0:15]
	s_waitcnt lgkmcnt(3)
	v_mfma_f32_32x32x16_bf16 v[32:47], v[112:115], v[152:155], v[32:47]
	s_waitcnt lgkmcnt(2)
	v_mfma_f32_32x32x16_bf16 v[0:15], v[116:119], v[152:155], v[0:15]
	s_waitcnt lgkmcnt(1)
	v_mfma_f32_32x32x16_bf16 v[32:47], v[120:123], v[156:159], v[32:47]
	s_waitcnt lgkmcnt(0)
	v_mfma_f32_32x32x16_bf16 v[0:15], v[124:127], v[156:159], v[0:15]
	s_setprio 0
	s_branch .LBB0_883
